# attention ks-loop rescheduled: K/V LDS reads prefetched, exp interleaved with MFMAs (no-stab fast path)
# speedup vs baseline: 1.0694x; 1.0694x over previous
; __device__ __forceinline__ uint32_t pack2(float a, float b) { uint32_t r; asm("v_cvt_pk_bf16_f32 %0, %1, %2" : "=v"(r) : "v"(a), "v"(b)); return r; }
; #define MFMA16(a, b, c) __builtin_amdgcn_mfma_f32_16x16x32_bf16(a, b, c, 0, 0, 0)
; __device__ __forceinline__ void attn_phase(const Params& p, char* smem) {
;     ...
;       if (active) {
;         const bf16_t* cK = Ks + buf * KT * KLD;
;         const bf16_t* cV = Vt + buf * 64 * VLD;
; #pragma unroll 1
;         for (int ks = 0; ks < 4; ++ks) {
;           uint32_t pfu[4][4];
; #pragma unroll
;           for (int kf = 0; kf < 2; ++kf) {
;             f32x4 sT[4];
; #pragma unroll
;             for (int g = 0; g < 4; ++g) sT[g] = (f32x4){0.f, 0.f, 0.f, 0.f};
; #pragma unroll
;             for (int ds = 0; ds < 3; ++ds) {
;               bf16x8 ka = *(const bf16x8*)(cK + (ks * 32 + kf * 16 + fr) * KLD + ds * 32 + fq * 8);
; #pragma unroll
;               for (int g = 0; g < 4; ++g) sT[g] = MFMA16(ka, qf[g][ds], sT[g]);
;             }
;             if (stab) {
; #pragma unroll
;               for (int g = 0; g < 4; ++g) { sT[g][0] += mneg[g]; sT[g][1] += mneg[g]; sT[g][2] += mneg[g]; sT[g][3] += mneg[g]; }
;             }
; #pragma unroll
;             for (int g = 0; g < 4; ++g) {
;               float p0 = __builtin_amdgcn_exp2f(sT[g][0]), p1 = __builtin_amdgcn_exp2f(sT[g][1]);
;               float p2 = __builtin_amdgcn_exp2f(sT[g][2]), p3 = __builtin_amdgcn_exp2f(sT[g][3]);
;               { float l_ = lrun[g]; l_ += p0; l_ += p1; l_ += p2; l_ += p3; lrun[g] = l_; }
;               pfu[g][kf * 2] = pack2(p0, p1); pfu[g][kf * 2 + 1] = pack2(p2, p3);
;             }
;           }
;           bf16x8 pf[4];
; #pragma unroll
;           for (int g = 0; g < 4; ++g) {
;             union { uint32_t u[4]; bf16x8 v; } cvt;
;             cvt.u[0] = pfu[g][0]; cvt.u[1] = pfu[g][1]; cvt.u[2] = pfu[g][2]; cvt.u[3] = pfu[g][3];
;             pf[g] = cvt.v;
;           }
; #pragma unroll
;           for (int dvf = 0; dvf < 4; ++dvf) {
;             const bf16_t* vp = cV + (dvf * 16 + fr) * VLD + ks * 32 + fq * 4;
;             union { uint2 u[2]; bf16x8 v; } va;
;             va.u[0] = *(const uint2*)(vp);
;             va.u[1] = *(const uint2*)(vp + 16);
; #pragma unroll
;             for (int g = 0; g < 4; ++g) oT[g][dvf] = MFMA16(va.v, pf[g], oT[g][dvf]);
;           }
;         }
.LBB0_413:
	s_and_saveexec_b64 s[10:11], s[40:41]
	s_cbranch_execz .LBB0_420
	v_cndmask_b32_e64 v132, 0, 1, s[6:7]
	s_movk_i32 s17, 0x4400
	v_mul_lo_u32 v133, v132, s17
	s_movk_i32 s17, 0x6800
	v_mul_lo_u32 v132, v132, s17
	v_add_u32_e32 v242, v240, v133
	v_add_u32_e32 v243, v241, v132
	s_mov_b32 s17, 4
	s_and_b64 vcc, exec, s[4:5]
	s_cbranch_vccnz .LBB0_416
	v_add_u32_e32 v206, 0xd000, v242
	ds_read_b128 v[132:135], v243
	ds_read_b128 v[136:139], v243 offset:64
	ds_read_b128 v[140:143], v243 offset:128
	s_mov_b32 s17, 3
.Lattn_fast_loop:
	ds_read_b128 v[148:151], v243 offset:3328
	ds_read_b128 v[152:155], v243 offset:3392
	ds_read_b128 v[156:159], v243 offset:3456
	s_waitcnt lgkmcnt(5)
	v_mfma_f32_16x16x32_bf16 v[244:247], v[132:135], v[0:3], 0
	v_mfma_f32_16x16x32_bf16 v[248:251], v[132:135], v[12:15], 0
	v_mfma_f32_16x16x32_bf16 v[208:211], v[132:135], v[24:27], 0
	v_mfma_f32_16x16x32_bf16 v[212:215], v[132:135], v[36:39], 0
	s_waitcnt lgkmcnt(4)
	v_mfma_f32_16x16x32_bf16 v[244:247], v[136:139], v[4:7], v[244:247]
	v_mfma_f32_16x16x32_bf16 v[248:251], v[136:139], v[16:19], v[248:251]
	v_mfma_f32_16x16x32_bf16 v[208:211], v[136:139], v[28:31], v[208:211]
	v_mfma_f32_16x16x32_bf16 v[212:215], v[136:139], v[40:43], v[212:215]
	s_waitcnt lgkmcnt(3)
	v_mfma_f32_16x16x32_bf16 v[244:247], v[140:143], v[8:11], v[244:247]
	v_mfma_f32_16x16x32_bf16 v[248:251], v[140:143], v[20:23], v[248:251]
	v_mfma_f32_16x16x32_bf16 v[208:211], v[140:143], v[32:35], v[208:211]
	v_mfma_f32_16x16x32_bf16 v[212:215], v[140:143], v[44:47], v[212:215]
	s_waitcnt lgkmcnt(2)
	v_mfma_f32_16x16x32_bf16 v[132:135], v[148:151], v[0:3], 0
	v_mfma_f32_16x16x32_bf16 v[136:139], v[148:151], v[12:15], 0
	v_mfma_f32_16x16x32_bf16 v[140:143], v[148:151], v[24:27], 0
	v_mfma_f32_16x16x32_bf16 v[144:147], v[148:151], v[36:39], 0
	s_waitcnt lgkmcnt(1)
	v_exp_f32_e32 v244, v244
	v_exp_f32_e32 v245, v245
	v_exp_f32_e32 v246, v246
	v_exp_f32_e32 v247, v247
	v_exp_f32_e32 v248, v248
	v_mfma_f32_16x16x32_bf16 v[132:135], v[152:155], v[4:7], v[132:135]
	v_exp_f32_e32 v249, v249
	v_exp_f32_e32 v250, v250
	v_exp_f32_e32 v251, v251
	v_add_f32_e32 v195, v195, v244
	v_add_f32_e32 v195, v195, v245
	v_mfma_f32_16x16x32_bf16 v[136:139], v[152:155], v[16:19], v[136:139]
	v_add_f32_e32 v195, v195, v246
	v_add_f32_e32 v195, v195, v247
	v_cvt_pk_bf16_f32 v244, v244, v245
	v_cvt_pk_bf16_f32 v245, v246, v247
	v_add_f32_e32 v194, v194, v248
	v_mfma_f32_16x16x32_bf16 v[140:143], v[152:155], v[28:31], v[140:143]
	v_add_f32_e32 v194, v194, v249
	v_add_f32_e32 v194, v194, v250
	v_add_f32_e32 v194, v194, v251
	v_cvt_pk_bf16_f32 v248, v248, v249
	v_cvt_pk_bf16_f32 v249, v250, v251
	v_mfma_f32_16x16x32_bf16 v[144:147], v[152:155], v[40:43], v[144:147]
	ds_read_b64 v[160:161], v206 offset:13056
	ds_read_b64 v[162:163], v206 offset:13088
	ds_read_b64 v[148:149], v206 offset:0
	ds_read_b64 v[150:151], v206 offset:32
	ds_read_b64 v[152:153], v206 offset:4352
	ds_read_b64 v[154:155], v206 offset:4384
	s_waitcnt lgkmcnt(6)
	v_exp_f32_e32 v208, v208
	v_exp_f32_e32 v209, v209
	v_exp_f32_e32 v210, v210
	v_exp_f32_e32 v211, v211
	v_exp_f32_e32 v212, v212
	v_mfma_f32_16x16x32_bf16 v[132:135], v[156:159], v[8:11], v[132:135]
	v_exp_f32_e32 v213, v213
	v_exp_f32_e32 v214, v214
	v_exp_f32_e32 v215, v215
	v_add_f32_e32 v191, v191, v208
	v_add_f32_e32 v191, v191, v209
	v_mfma_f32_16x16x32_bf16 v[136:139], v[156:159], v[20:23], v[136:139]
	v_add_f32_e32 v191, v191, v210
	v_add_f32_e32 v191, v191, v211
	v_cvt_pk_bf16_f32 v208, v208, v209
	v_cvt_pk_bf16_f32 v209, v210, v211
	v_add_f32_e32 v190, v190, v212
	v_mfma_f32_16x16x32_bf16 v[140:143], v[156:159], v[32:35], v[140:143]
	v_add_f32_e32 v190, v190, v213
	v_add_f32_e32 v190, v190, v214
	v_add_f32_e32 v190, v190, v215
	v_cvt_pk_bf16_f32 v212, v212, v213
	v_cvt_pk_bf16_f32 v213, v214, v215
	v_mfma_f32_16x16x32_bf16 v[144:147], v[156:159], v[44:47], v[144:147]
	ds_read_b64 v[156:157], v206 offset:8704
	ds_read_b64 v[158:159], v206 offset:8736
	v_add_u32_e32 v243, 0x1a00, v243
	v_exp_f32_e32 v132, v132
	v_exp_f32_e32 v133, v133
	v_exp_f32_e32 v134, v134
	v_exp_f32_e32 v135, v135
	v_add_f32_e32 v195, v195, v132
	v_add_f32_e32 v195, v195, v133
	v_add_f32_e32 v195, v195, v134
	v_add_f32_e32 v195, v195, v135
	v_cvt_pk_bf16_f32 v246, v132, v133
	v_cvt_pk_bf16_f32 v247, v134, v135
	ds_read_b128 v[132:135], v243
	s_waitcnt lgkmcnt(1)
	v_mfma_f32_16x16x32_bf16 v[108:111], v[148:151], v[244:247], v[108:111]
	v_exp_f32_e32 v136, v136
	v_exp_f32_e32 v137, v137
	v_exp_f32_e32 v138, v138
	v_mfma_f32_16x16x32_bf16 v[104:107], v[152:155], v[244:247], v[104:107]
	v_exp_f32_e32 v139, v139
	v_add_f32_e32 v194, v194, v136
	v_add_f32_e32 v194, v194, v137
	v_mfma_f32_16x16x32_bf16 v[100:103], v[156:159], v[244:247], v[100:103]
	v_add_f32_e32 v194, v194, v138
	v_add_f32_e32 v194, v194, v139
	v_cvt_pk_bf16_f32 v250, v136, v137
	v_cvt_pk_bf16_f32 v251, v138, v139
	v_mfma_f32_16x16x32_bf16 v[96:99], v[160:163], v[244:247], v[96:99]
	ds_read_b128 v[136:139], v243 offset:64
	v_mfma_f32_16x16x32_bf16 v[92:95], v[148:151], v[248:251], v[92:95]
	v_exp_f32_e32 v140, v140
	v_exp_f32_e32 v141, v141
	v_exp_f32_e32 v142, v142
	v_mfma_f32_16x16x32_bf16 v[88:91], v[152:155], v[248:251], v[88:91]
	v_exp_f32_e32 v143, v143
	v_add_f32_e32 v191, v191, v140
	v_add_f32_e32 v191, v191, v141
	v_mfma_f32_16x16x32_bf16 v[84:87], v[156:159], v[248:251], v[84:87]
	v_add_f32_e32 v191, v191, v142
	v_add_f32_e32 v191, v191, v143
	v_cvt_pk_bf16_f32 v210, v140, v141
	v_cvt_pk_bf16_f32 v211, v142, v143
	v_mfma_f32_16x16x32_bf16 v[80:83], v[160:163], v[248:251], v[80:83]
	ds_read_b128 v[140:143], v243 offset:128
	v_mfma_f32_16x16x32_bf16 v[76:79], v[148:151], v[208:211], v[76:79]
	v_exp_f32_e32 v144, v144
	v_exp_f32_e32 v145, v145
	v_exp_f32_e32 v146, v146
	v_mfma_f32_16x16x32_bf16 v[72:75], v[152:155], v[208:211], v[72:75]
	v_exp_f32_e32 v147, v147
	v_add_f32_e32 v190, v190, v144
	v_add_f32_e32 v190, v190, v145
	v_mfma_f32_16x16x32_bf16 v[68:71], v[156:159], v[208:211], v[68:71]
	v_add_f32_e32 v190, v190, v146
	v_add_f32_e32 v190, v190, v147
	v_cvt_pk_bf16_f32 v214, v144, v145
	v_cvt_pk_bf16_f32 v215, v146, v147
	v_mfma_f32_16x16x32_bf16 v[64:67], v[160:163], v[208:211], v[64:67]
	v_add_u32_e32 v206, 64, v206
	v_mfma_f32_16x16x32_bf16 v[60:63], v[148:151], v[212:215], v[60:63]
	v_mfma_f32_16x16x32_bf16 v[56:59], v[152:155], v[212:215], v[56:59]
	v_mfma_f32_16x16x32_bf16 v[52:55], v[156:159], v[212:215], v[52:55]
	v_mfma_f32_16x16x32_bf16 v[48:51], v[160:163], v[212:215], v[48:51]
	s_add_i32 s17, s17, -1
	s_cmp_lg_u32 s17, 0
	s_cbranch_scc1 .Lattn_fast_loop
; __device__ __forceinline__ uint32_t pack2(float a, float b) { uint32_t r; asm("v_cvt_pk_bf16_f32 %0, %1, %2" : "=v"(r) : "v"(a), "v"(b)); return r; }
; #define MFMA16(a, b, c) __builtin_amdgcn_mfma_f32_16x16x32_bf16(a, b, c, 0, 0, 0)
; __device__ __forceinline__ void attn_phase(const Params& p, char* smem) {
;     ...
;       if (active) {
;         const bf16_t* cK = Ks + buf * KT * KLD;
;         const bf16_t* cV = Vt + buf * 64 * VLD;
; #pragma unroll 1
;         for (int ks = 0; ks < 4; ++ks) {
;           uint32_t pfu[4][4];
; #pragma unroll
;           for (int kf = 0; kf < 2; ++kf) {
;             f32x4 sT[4];
; #pragma unroll
;             for (int g = 0; g < 4; ++g) sT[g] = (f32x4){0.f, 0.f, 0.f, 0.f};
; #pragma unroll
;             for (int ds = 0; ds < 3; ++ds) {
;               bf16x8 ka = *(const bf16x8*)(cK + (ks * 32 + kf * 16 + fr) * KLD + ds * 32 + fq * 8);
; #pragma unroll
;               for (int g = 0; g < 4; ++g) sT[g] = MFMA16(ka, qf[g][ds], sT[g]);
;             }
;             if (stab) {
; #pragma unroll
;               for (int g = 0; g < 4; ++g) { sT[g][0] += mneg[g]; sT[g][1] += mneg[g]; sT[g][2] += mneg[g]; sT[g][3] += mneg[g]; }
;             }
; #pragma unroll
;             for (int g = 0; g < 4; ++g) {
;               float p0 = __builtin_amdgcn_exp2f(sT[g][0]), p1 = __builtin_amdgcn_exp2f(sT[g][1]);
;               float p2 = __builtin_amdgcn_exp2f(sT[g][2]), p3 = __builtin_amdgcn_exp2f(sT[g][3]);
;               { float l_ = lrun[g]; l_ += p0; l_ += p1; l_ += p2; l_ += p3; lrun[g] = l_; }
;               pfu[g][kf * 2] = pack2(p0, p1); pfu[g][kf * 2 + 1] = pack2(p2, p3);
;             }
;           }
;           bf16x8 pf[4];
; #pragma unroll
;           for (int g = 0; g < 4; ++g) {
;             union { uint32_t u[4]; bf16x8 v; } cvt;
;             cvt.u[0] = pfu[g][0]; cvt.u[1] = pfu[g][1]; cvt.u[2] = pfu[g][2]; cvt.u[3] = pfu[g][3];
;             pf[g] = cvt.v;
;           }
; #pragma unroll
;           for (int dvf = 0; dvf < 4; ++dvf) {
;             const bf16_t* vp = cV + (dvf * 16 + fr) * VLD + ks * 32 + fq * 4;
;             union { uint2 u[2]; bf16x8 v; } va;
;             va.u[0] = *(const uint2*)(vp);
;             va.u[1] = *(const uint2*)(vp + 16);
; #pragma unroll
;             for (int g = 0; g < 4; ++g) oT[g][dvf] = MFMA16(va.v, pf[g], oT[g][dvf]);
;           }
;         }
	ds_read_b128 v[148:151], v243 offset:3328
	ds_read_b128 v[152:155], v243 offset:3392
	ds_read_b128 v[156:159], v243 offset:3456
	s_waitcnt lgkmcnt(5)
	v_mfma_f32_16x16x32_bf16 v[244:247], v[132:135], v[0:3], 0
	v_mfma_f32_16x16x32_bf16 v[248:251], v[132:135], v[12:15], 0
	v_mfma_f32_16x16x32_bf16 v[208:211], v[132:135], v[24:27], 0
	v_mfma_f32_16x16x32_bf16 v[212:215], v[132:135], v[36:39], 0
	s_waitcnt lgkmcnt(4)
	v_mfma_f32_16x16x32_bf16 v[244:247], v[136:139], v[4:7], v[244:247]
	v_mfma_f32_16x16x32_bf16 v[248:251], v[136:139], v[16:19], v[248:251]
	v_mfma_f32_16x16x32_bf16 v[208:211], v[136:139], v[28:31], v[208:211]
	v_mfma_f32_16x16x32_bf16 v[212:215], v[136:139], v[40:43], v[212:215]
	s_waitcnt lgkmcnt(3)
	v_mfma_f32_16x16x32_bf16 v[244:247], v[140:143], v[8:11], v[244:247]
	v_mfma_f32_16x16x32_bf16 v[248:251], v[140:143], v[20:23], v[248:251]
	v_mfma_f32_16x16x32_bf16 v[208:211], v[140:143], v[32:35], v[208:211]
	v_mfma_f32_16x16x32_bf16 v[212:215], v[140:143], v[44:47], v[212:215]
	s_waitcnt lgkmcnt(2)
	v_mfma_f32_16x16x32_bf16 v[132:135], v[148:151], v[0:3], 0
	v_mfma_f32_16x16x32_bf16 v[136:139], v[148:151], v[12:15], 0
	v_mfma_f32_16x16x32_bf16 v[140:143], v[148:151], v[24:27], 0
	v_mfma_f32_16x16x32_bf16 v[144:147], v[148:151], v[36:39], 0
	s_waitcnt lgkmcnt(1)
	v_exp_f32_e32 v244, v244
	v_exp_f32_e32 v245, v245
	v_exp_f32_e32 v246, v246
	v_exp_f32_e32 v247, v247
	v_exp_f32_e32 v248, v248
	v_mfma_f32_16x16x32_bf16 v[132:135], v[152:155], v[4:7], v[132:135]
	v_exp_f32_e32 v249, v249
	v_exp_f32_e32 v250, v250
	v_exp_f32_e32 v251, v251
	v_add_f32_e32 v195, v195, v244
	v_add_f32_e32 v195, v195, v245
	v_mfma_f32_16x16x32_bf16 v[136:139], v[152:155], v[16:19], v[136:139]
	v_add_f32_e32 v195, v195, v246
	v_add_f32_e32 v195, v195, v247
	v_cvt_pk_bf16_f32 v244, v244, v245
	v_cvt_pk_bf16_f32 v245, v246, v247
	v_add_f32_e32 v194, v194, v248
	v_mfma_f32_16x16x32_bf16 v[140:143], v[152:155], v[28:31], v[140:143]
	v_add_f32_e32 v194, v194, v249
	v_add_f32_e32 v194, v194, v250
	v_add_f32_e32 v194, v194, v251
	v_cvt_pk_bf16_f32 v248, v248, v249
	v_cvt_pk_bf16_f32 v249, v250, v251
	v_mfma_f32_16x16x32_bf16 v[144:147], v[152:155], v[40:43], v[144:147]
	ds_read_b64 v[160:161], v206 offset:13056
	ds_read_b64 v[162:163], v206 offset:13088
	ds_read_b64 v[148:149], v206 offset:0
	ds_read_b64 v[150:151], v206 offset:32
	ds_read_b64 v[152:153], v206 offset:4352
	ds_read_b64 v[154:155], v206 offset:4384
	s_waitcnt lgkmcnt(6)
	v_exp_f32_e32 v208, v208
	v_exp_f32_e32 v209, v209
	v_exp_f32_e32 v210, v210
	v_exp_f32_e32 v211, v211
	v_exp_f32_e32 v212, v212
	v_mfma_f32_16x16x32_bf16 v[132:135], v[156:159], v[8:11], v[132:135]
	v_exp_f32_e32 v213, v213
	v_exp_f32_e32 v214, v214
	v_exp_f32_e32 v215, v215
	v_add_f32_e32 v191, v191, v208
	v_add_f32_e32 v191, v191, v209
	v_mfma_f32_16x16x32_bf16 v[136:139], v[156:159], v[20:23], v[136:139]
	v_add_f32_e32 v191, v191, v210
	v_add_f32_e32 v191, v191, v211
	v_cvt_pk_bf16_f32 v208, v208, v209
	v_cvt_pk_bf16_f32 v209, v210, v211
	v_add_f32_e32 v190, v190, v212
	v_mfma_f32_16x16x32_bf16 v[140:143], v[156:159], v[32:35], v[140:143]
	v_add_f32_e32 v190, v190, v213
	v_add_f32_e32 v190, v190, v214
	v_add_f32_e32 v190, v190, v215
	v_cvt_pk_bf16_f32 v212, v212, v213
	v_cvt_pk_bf16_f32 v213, v214, v215
	v_mfma_f32_16x16x32_bf16 v[144:147], v[156:159], v[44:47], v[144:147]
	ds_read_b64 v[156:157], v206 offset:8704
	ds_read_b64 v[158:159], v206 offset:8736
	v_exp_f32_e32 v132, v132
	v_exp_f32_e32 v133, v133
	v_exp_f32_e32 v134, v134
	v_exp_f32_e32 v135, v135
	v_add_f32_e32 v195, v195, v132
	v_add_f32_e32 v195, v195, v133
	v_add_f32_e32 v195, v195, v134
	v_add_f32_e32 v195, v195, v135
	v_cvt_pk_bf16_f32 v246, v132, v133
	v_cvt_pk_bf16_f32 v247, v134, v135
	s_waitcnt lgkmcnt(0)
	s_nop 0
	v_mfma_f32_16x16x32_bf16 v[108:111], v[148:151], v[244:247], v[108:111]
	v_exp_f32_e32 v136, v136
	v_exp_f32_e32 v137, v137
	v_exp_f32_e32 v138, v138
	v_mfma_f32_16x16x32_bf16 v[104:107], v[152:155], v[244:247], v[104:107]
	v_exp_f32_e32 v139, v139
	v_add_f32_e32 v194, v194, v136
	v_add_f32_e32 v194, v194, v137
	v_mfma_f32_16x16x32_bf16 v[100:103], v[156:159], v[244:247], v[100:103]
	v_add_f32_e32 v194, v194, v138
	v_add_f32_e32 v194, v194, v139
	v_cvt_pk_bf16_f32 v250, v136, v137
	v_cvt_pk_bf16_f32 v251, v138, v139
	v_mfma_f32_16x16x32_bf16 v[96:99], v[160:163], v[244:247], v[96:99]
	s_nop 0
	v_mfma_f32_16x16x32_bf16 v[92:95], v[148:151], v[248:251], v[92:95]
	v_exp_f32_e32 v140, v140
	v_exp_f32_e32 v141, v141
	v_exp_f32_e32 v142, v142
	v_mfma_f32_16x16x32_bf16 v[88:91], v[152:155], v[248:251], v[88:91]
	v_exp_f32_e32 v143, v143
	v_add_f32_e32 v191, v191, v140
	v_add_f32_e32 v191, v191, v141
	v_mfma_f32_16x16x32_bf16 v[84:87], v[156:159], v[248:251], v[84:87]
	v_add_f32_e32 v191, v191, v142
	v_add_f32_e32 v191, v191, v143
	v_cvt_pk_bf16_f32 v210, v140, v141
	v_cvt_pk_bf16_f32 v211, v142, v143
	v_mfma_f32_16x16x32_bf16 v[80:83], v[160:163], v[248:251], v[80:83]
	s_nop 0
	v_mfma_f32_16x16x32_bf16 v[76:79], v[148:151], v[208:211], v[76:79]
	v_exp_f32_e32 v144, v144
	v_exp_f32_e32 v145, v145
	v_exp_f32_e32 v146, v146
	v_mfma_f32_16x16x32_bf16 v[72:75], v[152:155], v[208:211], v[72:75]
	v_exp_f32_e32 v147, v147
	v_add_f32_e32 v190, v190, v144
	v_add_f32_e32 v190, v190, v145
	v_mfma_f32_16x16x32_bf16 v[68:71], v[156:159], v[208:211], v[68:71]
	v_add_f32_e32 v190, v190, v146
	v_add_f32_e32 v190, v190, v147
	v_cvt_pk_bf16_f32 v214, v144, v145
	v_cvt_pk_bf16_f32 v215, v146, v147
	v_mfma_f32_16x16x32_bf16 v[64:67], v[160:163], v[208:211], v[64:67]
	s_nop 0
	v_mfma_f32_16x16x32_bf16 v[60:63], v[148:151], v[212:215], v[60:63]
	v_mfma_f32_16x16x32_bf16 v[56:59], v[152:155], v[212:215], v[56:59]
	v_mfma_f32_16x16x32_bf16 v[52:55], v[156:159], v[212:215], v[52:55]
	v_mfma_f32_16x16x32_bf16 v[48:51], v[160:163], v[212:215], v[48:51]
	s_branch .LBB0_420
